# seam leader issues its L2 invalidate after the release atomic instead of before it
# speedup vs baseline: 1.0054x; 1.0054x over previous
; __device__ __forceinline__ unsigned xb_ld(unsigned* p)              { return __hip_atomic_load(p, __ATOMIC_RELAXED, __HIP_MEMORY_SCOPE_AGENT); }
; __device__ __forceinline__ unsigned xb_add(unsigned* p, unsigned v) { return __hip_atomic_fetch_add(p, v, __ATOMIC_RELAXED, __HIP_MEMORY_SCOPE_AGENT); }
; #define XB_SPIN(cond, bar) do { unsigned _sp = 0; while (cond) { __builtin_amdgcn_s_sleep(1); \
;     if ((++_sp & 255u) == 0u) { if (xb_ld(&(bar)[XB_TMO])) break; if (_sp > XB_SPIN_CAP) { atomicAdd(&(bar)[XB_TMO], 1u); break; } } } } while (0)
; __device__ __forceinline__ void xcd_barrier(const XcdBarrier& b) {
;     asm volatile("s_waitcnt vmcnt(0)" ::: "memory");
;     __syncthreads();
;     if (threadIdx.x == 0) {
;         unsigned* bar = b.bar;
;         __builtin_amdgcn_s_waitcnt(0);
;         unsigned nloc = b.st[0], nx = b.st[1];
;         if (nloc == 0u) { xcd_barrier_complete(bar, b.x, nloc, nx); b.st[0] = nloc; b.st[1] = nx; }
;         const unsigned old = xb_add(&bar[XB_XSUB(b.x)], 1u);
;         const unsigned gen = old / nloc;
;         if (old + 1u == (gen + 1u) * nloc) {
;             __builtin_amdgcn_fence(__ATOMIC_RELEASE, "agent");
;             asm volatile("s_waitcnt vmcnt(0)" ::: "memory");
;             const unsigned og = xb_add(&bar[XB_TOP], 1u);
;             const unsigned tg = og / nx;
;             if (og + 1u == (tg + 1u) * nx) xb_add(&bar[XB_TOPGEN], 1u);
;             else XB_SPIN(xb_ld(&bar[XB_TOPGEN]) == tg, bar);
;             __builtin_amdgcn_fence(__ATOMIC_ACQUIRE, "agent");
;             xb_add(&bar[XB_XGEN(b.x)], 1u);
;             asm volatile("s_waitcnt vmcnt(0)" ::: "memory");
.LBB0_175:
	s_waitcnt vmcnt(0) lgkmcnt(0)
	s_barrier
	v_readlane_b32 s74, v252, 15
	v_readlane_b32 s75, v252, 16
	v_readfirstlane_b32 s98, v222
	s_nop 3
	s_cmp_lg_u32 s98, 0
	s_cbranch_scc1 .Lsm2_done
	v_mov_b32_e32 v0, 0x23fc0
	ds_read_b64 v[2:3], v0
	v_readlane_b32 s99, v252, 3
	s_add_u32 s100, s58, 0x507000
	s_addc_u32 s101, s59, 0
	s_lshl_b32 s99, s99, 8
	v_mov_b32_e32 v0, s99
	v_mov_b32_e32 v1, 1
	s_mov_b64 exec, 1
	s_nop 1
	global_atomic_add v4, v0, v1, s[100:101] sc0
	s_waitcnt vmcnt(0) lgkmcnt(0)
	v_readfirstlane_b32 s99, v4
	v_readfirstlane_b32 vcc_lo, v2
	v_readfirstlane_b32 vcc_hi, v3
	s_add_u32 s100, s58, 0x500080
	s_addc_u32 s101, s59, 0
	v_mov_b32_e32 v0, 0
	s_add_u32 s99, s99, 1
	s_mul_i32 s98, vcc_lo, 1
	s_cmp_lg_u32 s99, s98
	s_cbranch_scc1 .Lsm2_nl
	buffer_wbl2 sc1
	s_waitcnt vmcnt(0)
	global_atomic_add v0, v1, s[100:101]
	buffer_inv sc1
	s_branch .Lsm2_ld

; __device__ __forceinline__ unsigned xb_ld(unsigned* p)              { return __hip_atomic_load(p, __ATOMIC_RELAXED, __HIP_MEMORY_SCOPE_AGENT); }
; __device__ __forceinline__ unsigned xb_add(unsigned* p, unsigned v) { return __hip_atomic_fetch_add(p, v, __ATOMIC_RELAXED, __HIP_MEMORY_SCOPE_AGENT); }
; #define XB_SPIN(cond, bar) do { unsigned _sp = 0; while (cond) { __builtin_amdgcn_s_sleep(1); \
;     if ((++_sp & 255u) == 0u) { if (xb_ld(&(bar)[XB_TMO])) break; if (_sp > XB_SPIN_CAP) { atomicAdd(&(bar)[XB_TMO], 1u); break; } } } } while (0)
; __device__ __forceinline__ void xcd_barrier(const XcdBarrier& b) {
;     asm volatile("s_waitcnt vmcnt(0)" ::: "memory");
;     __syncthreads();
;     if (threadIdx.x == 0) {
;         unsigned* bar = b.bar;
;         __builtin_amdgcn_s_waitcnt(0);
;         unsigned nloc = b.st[0], nx = b.st[1];
;         if (nloc == 0u) { xcd_barrier_complete(bar, b.x, nloc, nx); b.st[0] = nloc; b.st[1] = nx; }
;         const unsigned old = xb_add(&bar[XB_XSUB(b.x)], 1u);
;         const unsigned gen = old / nloc;
;         if (old + 1u == (gen + 1u) * nloc) {
;             __builtin_amdgcn_fence(__ATOMIC_RELEASE, "agent");
;             asm volatile("s_waitcnt vmcnt(0)" ::: "memory");
;             const unsigned og = xb_add(&bar[XB_TOP], 1u);
;             const unsigned tg = og / nx;
;             if (og + 1u == (tg + 1u) * nx) xb_add(&bar[XB_TOPGEN], 1u);
;             else XB_SPIN(xb_ld(&bar[XB_TOPGEN]) == tg, bar);
;             __builtin_amdgcn_fence(__ATOMIC_ACQUIRE, "agent");
;             xb_add(&bar[XB_XGEN(b.x)], 1u);
;             asm volatile("s_waitcnt vmcnt(0)" ::: "memory");
.LBB0_335:
	s_waitcnt vmcnt(0) lgkmcnt(0)
	s_barrier
	v_readfirstlane_b32 s98, v222
	s_nop 3
	s_cmp_lg_u32 s98, 0
	s_cbranch_scc1 .Lsm3_done
	v_mov_b32_e32 v0, 0x23fc0
	ds_read_b64 v[2:3], v0
	v_readlane_b32 s99, v252, 3
	s_add_u32 s100, s58, 0x507000
	s_addc_u32 s101, s59, 0
	s_lshl_b32 s99, s99, 8
	v_mov_b32_e32 v0, s99
	v_mov_b32_e32 v1, 1
	s_mov_b64 exec, 1
	s_nop 1
	global_atomic_add v4, v0, v1, s[100:101] sc0
	s_waitcnt vmcnt(0) lgkmcnt(0)
	v_readfirstlane_b32 s99, v4
	v_readfirstlane_b32 vcc_lo, v2
	v_readfirstlane_b32 vcc_hi, v3
	s_add_u32 s100, s58, 0x500080
	s_addc_u32 s101, s59, 0
	v_mov_b32_e32 v0, 0
	s_add_u32 s99, s99, 1
	s_mul_i32 s98, vcc_lo, 2
	s_cmp_lg_u32 s99, s98
	s_cbranch_scc1 .Lsm3_nl
	buffer_wbl2 sc1
	s_waitcnt vmcnt(0)
	global_atomic_add v0, v1, s[100:101]
	buffer_inv sc1
	s_branch .Lsm3_ld

; __device__ __forceinline__ unsigned xb_ld(unsigned* p)              { return __hip_atomic_load(p, __ATOMIC_RELAXED, __HIP_MEMORY_SCOPE_AGENT); }
; __device__ __forceinline__ unsigned xb_add(unsigned* p, unsigned v) { return __hip_atomic_fetch_add(p, v, __ATOMIC_RELAXED, __HIP_MEMORY_SCOPE_AGENT); }
; #define XB_SPIN(cond, bar) do { unsigned _sp = 0; while (cond) { __builtin_amdgcn_s_sleep(1); \
;     if ((++_sp & 255u) == 0u) { if (xb_ld(&(bar)[XB_TMO])) break; if (_sp > XB_SPIN_CAP) { atomicAdd(&(bar)[XB_TMO], 1u); break; } } } } while (0)
; __device__ __forceinline__ void xcd_barrier(const XcdBarrier& b) {
;     asm volatile("s_waitcnt vmcnt(0)" ::: "memory");
;     __syncthreads();
;     if (threadIdx.x == 0) {
;         unsigned* bar = b.bar;
;         __builtin_amdgcn_s_waitcnt(0);
;         unsigned nloc = b.st[0], nx = b.st[1];
;         if (nloc == 0u) { xcd_barrier_complete(bar, b.x, nloc, nx); b.st[0] = nloc; b.st[1] = nx; }
;         const unsigned old = xb_add(&bar[XB_XSUB(b.x)], 1u);
;         const unsigned gen = old / nloc;
;         if (old + 1u == (gen + 1u) * nloc) {
;             __builtin_amdgcn_fence(__ATOMIC_RELEASE, "agent");
;             asm volatile("s_waitcnt vmcnt(0)" ::: "memory");
;             const unsigned og = xb_add(&bar[XB_TOP], 1u);
;             const unsigned tg = og / nx;
;             if (og + 1u == (tg + 1u) * nx) xb_add(&bar[XB_TOPGEN], 1u);
;             else XB_SPIN(xb_ld(&bar[XB_TOPGEN]) == tg, bar);
;             __builtin_amdgcn_fence(__ATOMIC_ACQUIRE, "agent");
;             xb_add(&bar[XB_XGEN(b.x)], 1u);
;             asm volatile("s_waitcnt vmcnt(0)" ::: "memory");
.LBB0_500:
	s_waitcnt vmcnt(0) lgkmcnt(0)
	s_barrier
	v_readfirstlane_b32 s98, v222
	s_nop 3
	s_cmp_lg_u32 s98, 0
	s_cbranch_scc1 .Lsm4_done
	v_mov_b32_e32 v0, 0x23fc0
	ds_read_b64 v[2:3], v0
	v_readlane_b32 s99, v252, 3
	s_add_u32 s100, s58, 0x507000
	s_addc_u32 s101, s59, 0
	s_lshl_b32 s99, s99, 8
	v_mov_b32_e32 v0, s99
	v_mov_b32_e32 v1, 1
	s_mov_b64 exec, 1
	s_nop 1
	global_atomic_add v4, v0, v1, s[100:101] sc0
	s_waitcnt vmcnt(0) lgkmcnt(0)
	v_readfirstlane_b32 s99, v4
	v_readfirstlane_b32 vcc_lo, v2
	v_readfirstlane_b32 vcc_hi, v3
	s_add_u32 s100, s58, 0x500080
	s_addc_u32 s101, s59, 0
	v_mov_b32_e32 v0, 0
	s_add_u32 s99, s99, 1
	s_mul_i32 s98, vcc_lo, 3
	s_cmp_lg_u32 s99, s98
	s_cbranch_scc1 .Lsm4_nl
	buffer_wbl2 sc1
	s_waitcnt vmcnt(0)
	global_atomic_add v0, v1, s[100:101]
	buffer_inv sc1
	s_branch .Lsm4_ld

; __device__ __forceinline__ unsigned xb_ld(unsigned* p)              { return __hip_atomic_load(p, __ATOMIC_RELAXED, __HIP_MEMORY_SCOPE_AGENT); }
; __device__ __forceinline__ unsigned xb_add(unsigned* p, unsigned v) { return __hip_atomic_fetch_add(p, v, __ATOMIC_RELAXED, __HIP_MEMORY_SCOPE_AGENT); }
; #define XB_SPIN(cond, bar) do { unsigned _sp = 0; while (cond) { __builtin_amdgcn_s_sleep(1); \
;     if ((++_sp & 255u) == 0u) { if (xb_ld(&(bar)[XB_TMO])) break; if (_sp > XB_SPIN_CAP) { atomicAdd(&(bar)[XB_TMO], 1u); break; } } } } while (0)
; __device__ __forceinline__ void xcd_barrier(const XcdBarrier& b) {
;     asm volatile("s_waitcnt vmcnt(0)" ::: "memory");
;     __syncthreads();
;     if (threadIdx.x == 0) {
;         unsigned* bar = b.bar;
;         __builtin_amdgcn_s_waitcnt(0);
;         unsigned nloc = b.st[0], nx = b.st[1];
;         if (nloc == 0u) { xcd_barrier_complete(bar, b.x, nloc, nx); b.st[0] = nloc; b.st[1] = nx; }
;         const unsigned old = xb_add(&bar[XB_XSUB(b.x)], 1u);
;         const unsigned gen = old / nloc;
;         if (old + 1u == (gen + 1u) * nloc) {
;             __builtin_amdgcn_fence(__ATOMIC_RELEASE, "agent");
;             asm volatile("s_waitcnt vmcnt(0)" ::: "memory");
;             const unsigned og = xb_add(&bar[XB_TOP], 1u);
;             const unsigned tg = og / nx;
;             if (og + 1u == (tg + 1u) * nx) xb_add(&bar[XB_TOPGEN], 1u);
;             else XB_SPIN(xb_ld(&bar[XB_TOPGEN]) == tg, bar);
;             __builtin_amdgcn_fence(__ATOMIC_ACQUIRE, "agent");
;             xb_add(&bar[XB_XGEN(b.x)], 1u);
;             asm volatile("s_waitcnt vmcnt(0)" ::: "memory");
.LBB0_715:
	s_waitcnt vmcnt(0) lgkmcnt(0)
	s_barrier
	v_readfirstlane_b32 s98, v222
	s_nop 3
	s_cmp_lg_u32 s98, 0
	s_cbranch_scc1 .Lsm5_done
	v_mov_b32_e32 v0, 0x23fc0
	ds_read_b64 v[2:3], v0
	v_readlane_b32 s99, v252, 3
	s_add_u32 s100, s58, 0x507000
	s_addc_u32 s101, s59, 0
	s_lshl_b32 s99, s99, 8
	v_mov_b32_e32 v0, s99
	v_mov_b32_e32 v1, 1
	s_mov_b64 exec, 1
	s_nop 1
	global_atomic_add v4, v0, v1, s[100:101] sc0
	s_waitcnt vmcnt(0) lgkmcnt(0)
	v_readfirstlane_b32 s99, v4
	v_readfirstlane_b32 vcc_lo, v2
	v_readfirstlane_b32 vcc_hi, v3
	s_add_u32 s100, s58, 0x500080
	s_addc_u32 s101, s59, 0
	v_mov_b32_e32 v0, 0
	s_add_u32 s99, s99, 1
	s_mul_i32 s98, vcc_lo, 4
	s_cmp_lg_u32 s99, s98
	s_cbranch_scc1 .Lsm5_nl
	buffer_wbl2 sc1
	s_waitcnt vmcnt(0)
	global_atomic_add v0, v1, s[100:101]
	buffer_inv sc1
	s_branch .Lsm5_ld

; __device__ __forceinline__ unsigned xb_ld(unsigned* p)              { return __hip_atomic_load(p, __ATOMIC_RELAXED, __HIP_MEMORY_SCOPE_AGENT); }
; __device__ __forceinline__ unsigned xb_add(unsigned* p, unsigned v) { return __hip_atomic_fetch_add(p, v, __ATOMIC_RELAXED, __HIP_MEMORY_SCOPE_AGENT); }
; #define XB_SPIN(cond, bar) do { unsigned _sp = 0; while (cond) { __builtin_amdgcn_s_sleep(1); \
;     if ((++_sp & 255u) == 0u) { if (xb_ld(&(bar)[XB_TMO])) break; if (_sp > XB_SPIN_CAP) { atomicAdd(&(bar)[XB_TMO], 1u); break; } } } } while (0)
; __device__ __forceinline__ void xcd_barrier(const XcdBarrier& b) {
;     asm volatile("s_waitcnt vmcnt(0)" ::: "memory");
;     __syncthreads();
;     if (threadIdx.x == 0) {
;         unsigned* bar = b.bar;
;         __builtin_amdgcn_s_waitcnt(0);
;         unsigned nloc = b.st[0], nx = b.st[1];
;         if (nloc == 0u) { xcd_barrier_complete(bar, b.x, nloc, nx); b.st[0] = nloc; b.st[1] = nx; }
;         const unsigned old = xb_add(&bar[XB_XSUB(b.x)], 1u);
;         const unsigned gen = old / nloc;
;         if (old + 1u == (gen + 1u) * nloc) {
;             __builtin_amdgcn_fence(__ATOMIC_RELEASE, "agent");
;             asm volatile("s_waitcnt vmcnt(0)" ::: "memory");
;             const unsigned og = xb_add(&bar[XB_TOP], 1u);
;             const unsigned tg = og / nx;
;             if (og + 1u == (tg + 1u) * nx) xb_add(&bar[XB_TOPGEN], 1u);
;             else XB_SPIN(xb_ld(&bar[XB_TOPGEN]) == tg, bar);
;             __builtin_amdgcn_fence(__ATOMIC_ACQUIRE, "agent");
;             xb_add(&bar[XB_XGEN(b.x)], 1u);
;             asm volatile("s_waitcnt vmcnt(0)" ::: "memory");
.LBB0_808:
	s_waitcnt vmcnt(0) lgkmcnt(0)
	s_barrier
	v_readfirstlane_b32 s98, v222
	s_nop 3
	s_cmp_lg_u32 s98, 0
	s_cbranch_scc1 .Lsm6_done
	v_mov_b32_e32 v0, 0x23fc0
	ds_read_b64 v[2:3], v0
	v_readlane_b32 s99, v252, 3
	s_add_u32 s100, s58, 0x507000
	s_addc_u32 s101, s59, 0
	s_lshl_b32 s99, s99, 8
	v_mov_b32_e32 v0, s99
	v_mov_b32_e32 v1, 1
	s_mov_b64 exec, 1
	s_nop 1
	global_atomic_add v4, v0, v1, s[100:101] sc0
	s_waitcnt vmcnt(0) lgkmcnt(0)
	v_readfirstlane_b32 s99, v4
	v_readfirstlane_b32 vcc_lo, v2
	v_readfirstlane_b32 vcc_hi, v3
	s_add_u32 s100, s58, 0x500080
	s_addc_u32 s101, s59, 0
	v_mov_b32_e32 v0, 0
	s_add_u32 s99, s99, 1
	s_mul_i32 s98, vcc_lo, 5
	s_cmp_lg_u32 s99, s98
	s_cbranch_scc1 .Lsm6_nl
	buffer_wbl2 sc1
	s_waitcnt vmcnt(0)
	global_atomic_add v0, v1, s[100:101]
	buffer_inv sc1
	s_branch .Lsm6_ld

; __device__ __forceinline__ unsigned xb_ld(unsigned* p)              { return __hip_atomic_load(p, __ATOMIC_RELAXED, __HIP_MEMORY_SCOPE_AGENT); }
; __device__ __forceinline__ unsigned xb_add(unsigned* p, unsigned v) { return __hip_atomic_fetch_add(p, v, __ATOMIC_RELAXED, __HIP_MEMORY_SCOPE_AGENT); }
; #define XB_SPIN(cond, bar) do { unsigned _sp = 0; while (cond) { __builtin_amdgcn_s_sleep(1); \
;     if ((++_sp & 255u) == 0u) { if (xb_ld(&(bar)[XB_TMO])) break; if (_sp > XB_SPIN_CAP) { atomicAdd(&(bar)[XB_TMO], 1u); break; } } } } while (0)
; __device__ __forceinline__ void xcd_barrier(const XcdBarrier& b) {
;     asm volatile("s_waitcnt vmcnt(0)" ::: "memory");
;     __syncthreads();
;     if (threadIdx.x == 0) {
;         unsigned* bar = b.bar;
;         __builtin_amdgcn_s_waitcnt(0);
;         unsigned nloc = b.st[0], nx = b.st[1];
;         if (nloc == 0u) { xcd_barrier_complete(bar, b.x, nloc, nx); b.st[0] = nloc; b.st[1] = nx; }
;         const unsigned old = xb_add(&bar[XB_XSUB(b.x)], 1u);
;         const unsigned gen = old / nloc;
;         if (old + 1u == (gen + 1u) * nloc) {
;             __builtin_amdgcn_fence(__ATOMIC_RELEASE, "agent");
;             asm volatile("s_waitcnt vmcnt(0)" ::: "memory");
;             const unsigned og = xb_add(&bar[XB_TOP], 1u);
;             const unsigned tg = og / nx;
;             if (og + 1u == (tg + 1u) * nx) xb_add(&bar[XB_TOPGEN], 1u);
;             else XB_SPIN(xb_ld(&bar[XB_TOPGEN]) == tg, bar);
;             __builtin_amdgcn_fence(__ATOMIC_ACQUIRE, "agent");
;             xb_add(&bar[XB_XGEN(b.x)], 1u);
;             asm volatile("s_waitcnt vmcnt(0)" ::: "memory");
.LBB0_963:
	s_waitcnt vmcnt(0) lgkmcnt(0)
	s_barrier
	v_readfirstlane_b32 s98, v222
	s_nop 3
	s_cmp_lg_u32 s98, 0
	s_cbranch_scc1 .Lsm7_done
	v_mov_b32_e32 v0, 0x23fc0
	ds_read_b64 v[2:3], v0
	v_readlane_b32 s99, v252, 3
	s_add_u32 s100, s58, 0x507000
	s_addc_u32 s101, s59, 0
	s_lshl_b32 s99, s99, 8
	v_mov_b32_e32 v0, s99
	v_mov_b32_e32 v1, 1
	s_mov_b64 exec, 1
	s_nop 1
	global_atomic_add v4, v0, v1, s[100:101] sc0
	s_waitcnt vmcnt(0) lgkmcnt(0)
	v_readfirstlane_b32 s99, v4
	v_readfirstlane_b32 vcc_lo, v2
	v_readfirstlane_b32 vcc_hi, v3
	s_add_u32 s100, s58, 0x500080
	s_addc_u32 s101, s59, 0
	v_mov_b32_e32 v0, 0
	s_add_u32 s99, s99, 1
	s_mul_i32 s98, vcc_lo, 6
	s_cmp_lg_u32 s99, s98
	s_cbranch_scc1 .Lsm7_nl
	buffer_wbl2 sc1
	s_waitcnt vmcnt(0)
	global_atomic_add v0, v1, s[100:101]
	buffer_inv sc1
	s_branch .Lsm7_ld

; __device__ __forceinline__ unsigned xb_ld(unsigned* p)              { return __hip_atomic_load(p, __ATOMIC_RELAXED, __HIP_MEMORY_SCOPE_AGENT); }
; __device__ __forceinline__ unsigned xb_add(unsigned* p, unsigned v) { return __hip_atomic_fetch_add(p, v, __ATOMIC_RELAXED, __HIP_MEMORY_SCOPE_AGENT); }
; #define XB_SPIN(cond, bar) do { unsigned _sp = 0; while (cond) { __builtin_amdgcn_s_sleep(1); \
;     if ((++_sp & 255u) == 0u) { if (xb_ld(&(bar)[XB_TMO])) break; if (_sp > XB_SPIN_CAP) { atomicAdd(&(bar)[XB_TMO], 1u); break; } } } } while (0)
; __device__ __forceinline__ void xcd_barrier(const XcdBarrier& b) {
;     asm volatile("s_waitcnt vmcnt(0)" ::: "memory");
;     __syncthreads();
;     if (threadIdx.x == 0) {
;         unsigned* bar = b.bar;
;         __builtin_amdgcn_s_waitcnt(0);
;         unsigned nloc = b.st[0], nx = b.st[1];
;         if (nloc == 0u) { xcd_barrier_complete(bar, b.x, nloc, nx); b.st[0] = nloc; b.st[1] = nx; }
;         const unsigned old = xb_add(&bar[XB_XSUB(b.x)], 1u);
;         const unsigned gen = old / nloc;
;         if (old + 1u == (gen + 1u) * nloc) {
;             __builtin_amdgcn_fence(__ATOMIC_RELEASE, "agent");
;             asm volatile("s_waitcnt vmcnt(0)" ::: "memory");
;             const unsigned og = xb_add(&bar[XB_TOP], 1u);
;             const unsigned tg = og / nx;
;             if (og + 1u == (tg + 1u) * nx) xb_add(&bar[XB_TOPGEN], 1u);
;             else XB_SPIN(xb_ld(&bar[XB_TOPGEN]) == tg, bar);
;             __builtin_amdgcn_fence(__ATOMIC_ACQUIRE, "agent");
;             xb_add(&bar[XB_XGEN(b.x)], 1u);
;             asm volatile("s_waitcnt vmcnt(0)" ::: "memory");
.LBB0_1035:
	s_waitcnt vmcnt(0) lgkmcnt(0)
	s_barrier
	v_readfirstlane_b32 s98, v222
	s_nop 3
	s_cmp_lg_u32 s98, 0
	s_cbranch_scc1 .Lsm8_done
	v_mov_b32_e32 v0, 0x23fc0
	ds_read_b64 v[2:3], v0
	v_readlane_b32 s99, v252, 3
	s_add_u32 s100, s58, 0x507000
	s_addc_u32 s101, s59, 0
	s_lshl_b32 s99, s99, 8
	v_mov_b32_e32 v0, s99
	v_mov_b32_e32 v1, 1
	s_mov_b64 exec, 1
	s_nop 1
	global_atomic_add v4, v0, v1, s[100:101] sc0
	s_waitcnt vmcnt(0) lgkmcnt(0)
	v_readfirstlane_b32 s99, v4
	v_readfirstlane_b32 vcc_lo, v2
	v_readfirstlane_b32 vcc_hi, v3
	s_add_u32 s100, s58, 0x500080
	s_addc_u32 s101, s59, 0
	v_mov_b32_e32 v0, 0
	s_add_u32 s99, s99, 1
	s_mul_i32 s98, vcc_lo, 7
	s_cmp_lg_u32 s99, s98
	s_cbranch_scc1 .Lsm8_nl
	buffer_wbl2 sc1
	s_waitcnt vmcnt(0)
	global_atomic_add v0, v1, s[100:101]
	buffer_inv sc1
	s_branch .Lsm8_ld
